# final RMSNorm fused into the last down-projection epilogue: the eight workgroups of a row block rendezvous on a counter word after adding their row sums of squares, then write the normalised output di
# speedup vs baseline: 1.0281x; 1.0145x over previous
.Lst_out_s9:
	v_lshl_add_u32 v215, s38, 8, v163
	v_add_u32_e32 v215, s26, v215
	v_lshlrev_b32_e32 v208, 2, v215
	v_lshl_add_u32 v212, v225, 3, s27
	v_lshl_add_u32 v212, s37, 8, v212
	v_lshl_add_u32 v209, v215, 11, v212
	v_lshlrev_b32_e32 v209, 1, v209
	v_lshlrev_b32_e32 v210, 1, v209
	v_lshlrev_b32_e32 v212, 2, v212
	v_lshl_add_u32 v215, v225, 4, v163
	v_xor_b32_e32 v213, 16, v215
	v_lshlrev_b32_e32 v213, 2, v213
	v_xor_b32_e32 v214, 32, v215
	v_lshlrev_b32_e32 v214, 2, v214
	v_add_u32_e32 v211, 0x0, v209
	global_load_dwordx4 v[176:179], v211, s[80:81]
	global_load_dwordx4 v[180:183], v211, s[80:81] offset:256
	v_add_u32_e32 v211, 0x10000, v209
	global_load_dwordx4 v[184:187], v211, s[80:81]
	global_load_dwordx4 v[188:191], v211, s[80:81] offset:256
	v_add_u32_e32 v211, 0x20000, v209
	global_load_dwordx4 v[192:195], v211, s[80:81]
	global_load_dwordx4 v[196:199], v211, s[80:81] offset:256
	s_waitcnt vmcnt(4)
	v_lshlrev_b32_e32 v200, 16, v176
	v_and_b32_e32 v201, 0xffff0000, v176
	v_lshlrev_b32_e32 v202, 16, v177
	v_and_b32_e32 v203, 0xffff0000, v177
	v_lshlrev_b32_e32 v204, 16, v178
	v_and_b32_e32 v205, 0xffff0000, v178
	v_lshlrev_b32_e32 v206, 16, v179
	v_and_b32_e32 v207, 0xffff0000, v179
	v_pk_add_f32 v[124:125], v[124:125], v[200:201]
	v_pk_add_f32 v[126:127], v[126:127], v[202:203]
	v_pk_add_f32 v[120:121], v[120:121], v[204:205]
	v_pk_add_f32 v[122:123], v[122:123], v[206:207]
	v_lshlrev_b32_e32 v200, 16, v180
	v_and_b32_e32 v201, 0xffff0000, v180
	v_lshlrev_b32_e32 v202, 16, v181
	v_and_b32_e32 v203, 0xffff0000, v181
	v_lshlrev_b32_e32 v204, 16, v182
	v_and_b32_e32 v205, 0xffff0000, v182
	v_lshlrev_b32_e32 v206, 16, v183
	v_and_b32_e32 v207, 0xffff0000, v183
	v_pk_add_f32 v[116:117], v[116:117], v[200:201]
	v_pk_add_f32 v[118:119], v[118:119], v[202:203]
	v_pk_add_f32 v[112:113], v[112:113], v[204:205]
	v_pk_add_f32 v[114:115], v[114:115], v[206:207]
	v_add_u32_e32 v211, 0x30000, v209
	global_load_dwordx4 v[176:179], v211, s[80:81]
	global_load_dwordx4 v[180:183], v211, s[80:81] offset:256
	s_waitcnt vmcnt(4)
	v_lshlrev_b32_e32 v200, 16, v184
	v_and_b32_e32 v201, 0xffff0000, v184
	v_lshlrev_b32_e32 v202, 16, v185
	v_and_b32_e32 v203, 0xffff0000, v185
	v_lshlrev_b32_e32 v204, 16, v186
	v_and_b32_e32 v205, 0xffff0000, v186
	v_lshlrev_b32_e32 v206, 16, v187
	v_and_b32_e32 v207, 0xffff0000, v187
	v_pk_add_f32 v[108:109], v[108:109], v[200:201]
	v_pk_add_f32 v[110:111], v[110:111], v[202:203]
	v_pk_add_f32 v[104:105], v[104:105], v[204:205]
	v_pk_add_f32 v[106:107], v[106:107], v[206:207]
	v_lshlrev_b32_e32 v200, 16, v188
	v_and_b32_e32 v201, 0xffff0000, v188
	v_lshlrev_b32_e32 v202, 16, v189
	v_and_b32_e32 v203, 0xffff0000, v189
	v_lshlrev_b32_e32 v204, 16, v190
	v_and_b32_e32 v205, 0xffff0000, v190
	v_lshlrev_b32_e32 v206, 16, v191
	v_and_b32_e32 v207, 0xffff0000, v191
	v_pk_add_f32 v[100:101], v[100:101], v[200:201]
	v_pk_add_f32 v[102:103], v[102:103], v[202:203]
	v_pk_add_f32 v[96:97], v[96:97], v[204:205]
	v_pk_add_f32 v[98:99], v[98:99], v[206:207]
	v_add_u32_e32 v211, 0x80000, v209
	global_load_dwordx4 v[184:187], v211, s[80:81]
	global_load_dwordx4 v[188:191], v211, s[80:81] offset:256
	s_waitcnt vmcnt(4)
	v_lshlrev_b32_e32 v200, 16, v192
	v_and_b32_e32 v201, 0xffff0000, v192
	v_lshlrev_b32_e32 v202, 16, v193
	v_and_b32_e32 v203, 0xffff0000, v193
	v_lshlrev_b32_e32 v204, 16, v194
	v_and_b32_e32 v205, 0xffff0000, v194
	v_lshlrev_b32_e32 v206, 16, v195
	v_and_b32_e32 v207, 0xffff0000, v195
	v_pk_add_f32 v[92:93], v[92:93], v[200:201]
	v_pk_add_f32 v[94:95], v[94:95], v[202:203]
	v_pk_add_f32 v[88:89], v[88:89], v[204:205]
	v_pk_add_f32 v[90:91], v[90:91], v[206:207]
	v_lshlrev_b32_e32 v200, 16, v196
	v_and_b32_e32 v201, 0xffff0000, v196
	v_lshlrev_b32_e32 v202, 16, v197
	v_and_b32_e32 v203, 0xffff0000, v197
	v_lshlrev_b32_e32 v204, 16, v198
	v_and_b32_e32 v205, 0xffff0000, v198
	v_lshlrev_b32_e32 v206, 16, v199
	v_and_b32_e32 v207, 0xffff0000, v199
	v_pk_add_f32 v[84:85], v[84:85], v[200:201]
	v_pk_add_f32 v[86:87], v[86:87], v[202:203]
	v_pk_add_f32 v[80:81], v[80:81], v[204:205]
	v_pk_add_f32 v[82:83], v[82:83], v[206:207]
	v_add_u32_e32 v211, 0x90000, v209
	global_load_dwordx4 v[192:195], v211, s[80:81]
	global_load_dwordx4 v[196:199], v211, s[80:81] offset:256
	s_waitcnt vmcnt(4)
	v_lshlrev_b32_e32 v200, 16, v176
	v_and_b32_e32 v201, 0xffff0000, v176
	v_lshlrev_b32_e32 v202, 16, v177
	v_and_b32_e32 v203, 0xffff0000, v177
	v_lshlrev_b32_e32 v204, 16, v178
	v_and_b32_e32 v205, 0xffff0000, v178
	v_lshlrev_b32_e32 v206, 16, v179
	v_and_b32_e32 v207, 0xffff0000, v179
	v_pk_add_f32 v[76:77], v[76:77], v[200:201]
	v_pk_add_f32 v[78:79], v[78:79], v[202:203]
	v_pk_add_f32 v[72:73], v[72:73], v[204:205]
	v_pk_add_f32 v[74:75], v[74:75], v[206:207]
	v_lshlrev_b32_e32 v200, 16, v180
	v_and_b32_e32 v201, 0xffff0000, v180
	v_lshlrev_b32_e32 v202, 16, v181
	v_and_b32_e32 v203, 0xffff0000, v181
	v_lshlrev_b32_e32 v204, 16, v182
	v_and_b32_e32 v205, 0xffff0000, v182
	v_lshlrev_b32_e32 v206, 16, v183
	v_and_b32_e32 v207, 0xffff0000, v183
	v_pk_add_f32 v[68:69], v[68:69], v[200:201]
	v_pk_add_f32 v[70:71], v[70:71], v[202:203]
	v_pk_add_f32 v[64:65], v[64:65], v[204:205]
	v_pk_add_f32 v[66:67], v[66:67], v[206:207]
	v_add_u32_e32 v211, 0xa0000, v209
	global_load_dwordx4 v[176:179], v211, s[80:81]
	global_load_dwordx4 v[180:183], v211, s[80:81] offset:256
	s_waitcnt vmcnt(4)
	v_lshlrev_b32_e32 v200, 16, v184
	v_and_b32_e32 v201, 0xffff0000, v184
	v_lshlrev_b32_e32 v202, 16, v185
	v_and_b32_e32 v203, 0xffff0000, v185
	v_lshlrev_b32_e32 v204, 16, v186
	v_and_b32_e32 v205, 0xffff0000, v186
	v_lshlrev_b32_e32 v206, 16, v187
	v_and_b32_e32 v207, 0xffff0000, v187
	v_pk_add_f32 v[60:61], v[60:61], v[200:201]
	v_pk_add_f32 v[62:63], v[62:63], v[202:203]
	v_pk_add_f32 v[56:57], v[56:57], v[204:205]
	v_pk_add_f32 v[58:59], v[58:59], v[206:207]
	v_lshlrev_b32_e32 v200, 16, v188
	v_and_b32_e32 v201, 0xffff0000, v188
	v_lshlrev_b32_e32 v202, 16, v189
	v_and_b32_e32 v203, 0xffff0000, v189
	v_lshlrev_b32_e32 v204, 16, v190
	v_and_b32_e32 v205, 0xffff0000, v190
	v_lshlrev_b32_e32 v206, 16, v191
	v_and_b32_e32 v207, 0xffff0000, v191
	v_pk_add_f32 v[52:53], v[52:53], v[200:201]
	v_pk_add_f32 v[54:55], v[54:55], v[202:203]
	v_pk_add_f32 v[48:49], v[48:49], v[204:205]
	v_pk_add_f32 v[50:51], v[50:51], v[206:207]
	v_add_u32_e32 v211, 0xb0000, v209
	global_load_dwordx4 v[184:187], v211, s[80:81]
	global_load_dwordx4 v[188:191], v211, s[80:81] offset:256
	s_waitcnt vmcnt(4)
	v_lshlrev_b32_e32 v200, 16, v192
	v_and_b32_e32 v201, 0xffff0000, v192
	v_lshlrev_b32_e32 v202, 16, v193
	v_and_b32_e32 v203, 0xffff0000, v193
	v_lshlrev_b32_e32 v204, 16, v194
	v_and_b32_e32 v205, 0xffff0000, v194
	v_lshlrev_b32_e32 v206, 16, v195
	v_and_b32_e32 v207, 0xffff0000, v195
	v_pk_add_f32 v[44:45], v[44:45], v[200:201]
	v_pk_add_f32 v[46:47], v[46:47], v[202:203]
	v_pk_add_f32 v[40:41], v[40:41], v[204:205]
	v_pk_add_f32 v[42:43], v[42:43], v[206:207]
	v_lshlrev_b32_e32 v200, 16, v196
	v_and_b32_e32 v201, 0xffff0000, v196
	v_lshlrev_b32_e32 v202, 16, v197
	v_and_b32_e32 v203, 0xffff0000, v197
	v_lshlrev_b32_e32 v204, 16, v198
	v_and_b32_e32 v205, 0xffff0000, v198
	v_lshlrev_b32_e32 v206, 16, v199
	v_and_b32_e32 v207, 0xffff0000, v199
	v_pk_add_f32 v[36:37], v[36:37], v[200:201]
	v_pk_add_f32 v[38:39], v[38:39], v[202:203]
	v_pk_add_f32 v[32:33], v[32:33], v[204:205]
	v_pk_add_f32 v[34:35], v[34:35], v[206:207]
	s_waitcnt vmcnt(2)
	v_lshlrev_b32_e32 v200, 16, v176
	v_and_b32_e32 v201, 0xffff0000, v176
	v_lshlrev_b32_e32 v202, 16, v177
	v_and_b32_e32 v203, 0xffff0000, v177
	v_lshlrev_b32_e32 v204, 16, v178
	v_and_b32_e32 v205, 0xffff0000, v178
	v_lshlrev_b32_e32 v206, 16, v179
	v_and_b32_e32 v207, 0xffff0000, v179
	v_pk_add_f32 v[28:29], v[28:29], v[200:201]
	v_pk_add_f32 v[30:31], v[30:31], v[202:203]
	v_pk_add_f32 v[24:25], v[24:25], v[204:205]
	v_pk_add_f32 v[26:27], v[26:27], v[206:207]
	v_lshlrev_b32_e32 v200, 16, v180
	v_and_b32_e32 v201, 0xffff0000, v180
	v_lshlrev_b32_e32 v202, 16, v181
	v_and_b32_e32 v203, 0xffff0000, v181
	v_lshlrev_b32_e32 v204, 16, v182
	v_and_b32_e32 v205, 0xffff0000, v182
	v_lshlrev_b32_e32 v206, 16, v183
	v_and_b32_e32 v207, 0xffff0000, v183
	v_pk_add_f32 v[20:21], v[20:21], v[200:201]
	v_pk_add_f32 v[22:23], v[22:23], v[202:203]
	v_pk_add_f32 v[16:17], v[16:17], v[204:205]
	v_pk_add_f32 v[18:19], v[18:19], v[206:207]
	s_waitcnt vmcnt(0)
	v_lshlrev_b32_e32 v200, 16, v184
	v_and_b32_e32 v201, 0xffff0000, v184
	v_lshlrev_b32_e32 v202, 16, v185
	v_and_b32_e32 v203, 0xffff0000, v185
	v_lshlrev_b32_e32 v204, 16, v186
	v_and_b32_e32 v205, 0xffff0000, v186
	v_lshlrev_b32_e32 v206, 16, v187
	v_and_b32_e32 v207, 0xffff0000, v187
	v_pk_add_f32 v[12:13], v[12:13], v[200:201]
	v_pk_add_f32 v[14:15], v[14:15], v[202:203]
	v_pk_add_f32 v[8:9], v[8:9], v[204:205]
	v_pk_add_f32 v[10:11], v[10:11], v[206:207]
	v_lshlrev_b32_e32 v200, 16, v188
	v_and_b32_e32 v201, 0xffff0000, v188
	v_lshlrev_b32_e32 v202, 16, v189
	v_and_b32_e32 v203, 0xffff0000, v189
	v_lshlrev_b32_e32 v204, 16, v190
	v_and_b32_e32 v205, 0xffff0000, v190
	v_lshlrev_b32_e32 v206, 16, v191
	v_and_b32_e32 v207, 0xffff0000, v191
	v_pk_add_f32 v[4:5], v[4:5], v[200:201]
	v_pk_add_f32 v[6:7], v[6:7], v[202:203]
	v_pk_add_f32 v[0:1], v[0:1], v[204:205]
	v_pk_add_f32 v[2:3], v[2:3], v[206:207]
	v_mul_f32_e32 v200, v124, v124
	v_fmac_f32_e32 v200, v125, v125
	v_fmac_f32_e32 v200, v126, v126
	v_fmac_f32_e32 v200, v127, v127
	v_fmac_f32_e32 v200, v120, v120
	v_fmac_f32_e32 v200, v121, v121
	v_fmac_f32_e32 v200, v122, v122
	v_fmac_f32_e32 v200, v123, v123
	v_fmac_f32_e32 v200, v116, v116
	v_fmac_f32_e32 v200, v117, v117
	v_fmac_f32_e32 v200, v118, v118
	v_fmac_f32_e32 v200, v119, v119
	v_fmac_f32_e32 v200, v112, v112
	v_fmac_f32_e32 v200, v113, v113
	v_fmac_f32_e32 v200, v114, v114
	v_fmac_f32_e32 v200, v115, v115
	v_mul_f32_e32 v201, v108, v108
	v_fmac_f32_e32 v201, v109, v109
	v_fmac_f32_e32 v201, v110, v110
	v_fmac_f32_e32 v201, v111, v111
	v_fmac_f32_e32 v201, v104, v104
	v_fmac_f32_e32 v201, v105, v105
	v_fmac_f32_e32 v201, v106, v106
	v_fmac_f32_e32 v201, v107, v107
	v_fmac_f32_e32 v201, v100, v100
	v_fmac_f32_e32 v201, v101, v101
	v_fmac_f32_e32 v201, v102, v102
	v_fmac_f32_e32 v201, v103, v103
	v_fmac_f32_e32 v201, v96, v96
	v_fmac_f32_e32 v201, v97, v97
	v_fmac_f32_e32 v201, v98, v98
	v_fmac_f32_e32 v201, v99, v99
	v_mul_f32_e32 v202, v92, v92
	v_fmac_f32_e32 v202, v93, v93
	v_fmac_f32_e32 v202, v94, v94
	v_fmac_f32_e32 v202, v95, v95
	v_fmac_f32_e32 v202, v88, v88
	v_fmac_f32_e32 v202, v89, v89
	v_fmac_f32_e32 v202, v90, v90
	v_fmac_f32_e32 v202, v91, v91
	v_fmac_f32_e32 v202, v84, v84
	v_fmac_f32_e32 v202, v85, v85
	v_fmac_f32_e32 v202, v86, v86
	v_fmac_f32_e32 v202, v87, v87
	v_fmac_f32_e32 v202, v80, v80
	v_fmac_f32_e32 v202, v81, v81
	v_fmac_f32_e32 v202, v82, v82
	v_fmac_f32_e32 v202, v83, v83
	v_mul_f32_e32 v203, v76, v76
	v_fmac_f32_e32 v203, v77, v77
	v_fmac_f32_e32 v203, v78, v78
	v_fmac_f32_e32 v203, v79, v79
	v_fmac_f32_e32 v203, v72, v72
	v_fmac_f32_e32 v203, v73, v73
	v_fmac_f32_e32 v203, v74, v74
	v_fmac_f32_e32 v203, v75, v75
	v_fmac_f32_e32 v203, v68, v68
	v_fmac_f32_e32 v203, v69, v69
	v_fmac_f32_e32 v203, v70, v70
	v_fmac_f32_e32 v203, v71, v71
	v_fmac_f32_e32 v203, v64, v64
	v_fmac_f32_e32 v203, v65, v65
	v_fmac_f32_e32 v203, v66, v66
	v_fmac_f32_e32 v203, v67, v67
	v_mul_f32_e32 v204, v60, v60
	v_fmac_f32_e32 v204, v61, v61
	v_fmac_f32_e32 v204, v62, v62
	v_fmac_f32_e32 v204, v63, v63
	v_fmac_f32_e32 v204, v56, v56
	v_fmac_f32_e32 v204, v57, v57
	v_fmac_f32_e32 v204, v58, v58
	v_fmac_f32_e32 v204, v59, v59
	v_fmac_f32_e32 v204, v52, v52
	v_fmac_f32_e32 v204, v53, v53
	v_fmac_f32_e32 v204, v54, v54
	v_fmac_f32_e32 v204, v55, v55
	v_fmac_f32_e32 v204, v48, v48
	v_fmac_f32_e32 v204, v49, v49
	v_fmac_f32_e32 v204, v50, v50
	v_fmac_f32_e32 v204, v51, v51
	v_mul_f32_e32 v205, v44, v44
	v_fmac_f32_e32 v205, v45, v45
	v_fmac_f32_e32 v205, v46, v46
	v_fmac_f32_e32 v205, v47, v47
	v_fmac_f32_e32 v205, v40, v40
	v_fmac_f32_e32 v205, v41, v41
	v_fmac_f32_e32 v205, v42, v42
	v_fmac_f32_e32 v205, v43, v43
	v_fmac_f32_e32 v205, v36, v36
	v_fmac_f32_e32 v205, v37, v37
	v_fmac_f32_e32 v205, v38, v38
	v_fmac_f32_e32 v205, v39, v39
	v_fmac_f32_e32 v205, v32, v32
	v_fmac_f32_e32 v205, v33, v33
	v_fmac_f32_e32 v205, v34, v34
	v_fmac_f32_e32 v205, v35, v35
	v_mul_f32_e32 v206, v28, v28
	v_fmac_f32_e32 v206, v29, v29
	v_fmac_f32_e32 v206, v30, v30
	v_fmac_f32_e32 v206, v31, v31
	v_fmac_f32_e32 v206, v24, v24
	v_fmac_f32_e32 v206, v25, v25
	v_fmac_f32_e32 v206, v26, v26
	v_fmac_f32_e32 v206, v27, v27
	v_fmac_f32_e32 v206, v20, v20
	v_fmac_f32_e32 v206, v21, v21
	v_fmac_f32_e32 v206, v22, v22
	v_fmac_f32_e32 v206, v23, v23
	v_fmac_f32_e32 v206, v16, v16
	v_fmac_f32_e32 v206, v17, v17
	v_fmac_f32_e32 v206, v18, v18
	v_fmac_f32_e32 v206, v19, v19
	v_mul_f32_e32 v207, v12, v12
	v_fmac_f32_e32 v207, v13, v13
	v_fmac_f32_e32 v207, v14, v14
	v_fmac_f32_e32 v207, v15, v15
	v_fmac_f32_e32 v207, v8, v8
	v_fmac_f32_e32 v207, v9, v9
	v_fmac_f32_e32 v207, v10, v10
	v_fmac_f32_e32 v207, v11, v11
	v_fmac_f32_e32 v207, v4, v4
	v_fmac_f32_e32 v207, v5, v5
	v_fmac_f32_e32 v207, v6, v6
	v_fmac_f32_e32 v207, v7, v7
	v_fmac_f32_e32 v207, v0, v0
	v_fmac_f32_e32 v207, v1, v1
	v_fmac_f32_e32 v207, v2, v2
	v_fmac_f32_e32 v207, v3, v3
	s_nop 1
	ds_bpermute_b32 v192, v213, v200
	ds_bpermute_b32 v193, v213, v201
	ds_bpermute_b32 v194, v213, v202
	ds_bpermute_b32 v195, v213, v203
	ds_bpermute_b32 v196, v213, v204
	ds_bpermute_b32 v197, v213, v205
	ds_bpermute_b32 v198, v213, v206
	ds_bpermute_b32 v199, v213, v207
	s_waitcnt lgkmcnt(0)
	v_add_f32_e32 v200, v200, v192
	v_add_f32_e32 v201, v201, v193
	v_add_f32_e32 v202, v202, v194
	v_add_f32_e32 v203, v203, v195
	v_add_f32_e32 v204, v204, v196
	v_add_f32_e32 v205, v205, v197
	v_add_f32_e32 v206, v206, v198
	v_add_f32_e32 v207, v207, v199
	ds_bpermute_b32 v192, v214, v200
	ds_bpermute_b32 v193, v214, v201
	ds_bpermute_b32 v194, v214, v202
	ds_bpermute_b32 v195, v214, v203
	ds_bpermute_b32 v196, v214, v204
	ds_bpermute_b32 v197, v214, v205
	ds_bpermute_b32 v198, v214, v206
	ds_bpermute_b32 v199, v214, v207
	s_waitcnt lgkmcnt(0)
	v_add_f32_e32 v200, v200, v192
	v_add_f32_e32 v201, v201, v193
	v_add_f32_e32 v202, v202, v194
	v_add_f32_e32 v203, v203, v195
	v_add_f32_e32 v204, v204, v196
	v_add_f32_e32 v205, v205, v197
	v_add_f32_e32 v206, v206, v198
	v_add_f32_e32 v207, v207, v199
	s_mov_b64 exec, 0xffff
	global_atomic_add_f32 v208, v200, s[10:11]
	global_atomic_add_f32 v208, v201, s[10:11] offset:64
	global_atomic_add_f32 v208, v202, s[10:11] offset:128
	global_atomic_add_f32 v208, v203, s[10:11] offset:192
	global_atomic_add_f32 v208, v204, s[10:11] offset:512
	global_atomic_add_f32 v208, v205, s[10:11] offset:576
	global_atomic_add_f32 v208, v206, s[10:11] offset:640
	global_atomic_add_f32 v208, v207, s[10:11] offset:704
	s_mov_b64 exec, -1
	s_waitcnt vmcnt(0)
	s_barrier
	s_add_u32 s98, s92, 0x80000
	s_addc_u32 s99, s93, 0
	s_cmpk_gt_u32 s3, 0x3f
	s_cbranch_scc1 .Lff_wait
	v_mov_b32_e32 v200, s38
	v_lshlrev_b32_e32 v200, 2, v200
	v_mov_b32_e32 v202, 1
	s_mov_b64 exec, 1
	global_atomic_add v200, v202, s[98:99]
	s_movk_i32 s101, 0x7d0
.Lff_spin:
	global_load_dword v201, v200, s[98:99] sc1
	s_waitcnt vmcnt(0)
	v_readfirstlane_b32 s100, v201
	s_cmp_gt_u32 s100, 7
	s_cbranch_scc1 .Lff_go
	s_sleep 1
	s_sub_u32 s101, s101, 1
	s_cmp_lg_u32 s101, 0
	s_cbranch_scc1 .Lff_spin
.Lff_go:
	s_mov_b64 exec, -1
.Lff_wait:
	s_barrier
	global_load_dword v176, v208, s[10:11] sc1
	global_load_dword v177, v208, s[10:11] offset:64 sc1
	global_load_dword v178, v208, s[10:11] offset:128 sc1
	global_load_dword v179, v208, s[10:11] offset:192 sc1
	global_load_dword v180, v208, s[10:11] offset:512 sc1
	global_load_dword v181, v208, s[10:11] offset:576 sc1
	global_load_dword v182, v208, s[10:11] offset:640 sc1
	global_load_dword v183, v208, s[10:11] offset:704 sc1
	global_load_dwordx4 v[184:187], v212, s[88:89] offset:0
	global_load_dwordx4 v[188:191], v212, s[88:89] offset:16
	global_load_dwordx4 v[192:195], v212, s[88:89] offset:512
	global_load_dwordx4 v[196:199], v212, s[88:89] offset:528
	v_mov_b32_e32 v215, 0x3727c5ac
	s_waitcnt vmcnt(0)
	v_fmamk_f32 v176, v176, 0x3a000000, v215
	v_fmamk_f32 v177, v177, 0x3a000000, v215
	v_fmamk_f32 v178, v178, 0x3a000000, v215
	v_fmamk_f32 v179, v179, 0x3a000000, v215
	v_fmamk_f32 v180, v180, 0x3a000000, v215
	v_fmamk_f32 v181, v181, 0x3a000000, v215
	v_fmamk_f32 v182, v182, 0x3a000000, v215
	v_fmamk_f32 v183, v183, 0x3a000000, v215
	v_rsq_f32_e32 v176, v176
	v_rsq_f32_e32 v177, v177
	v_rsq_f32_e32 v178, v178
	v_rsq_f32_e32 v179, v179
	v_rsq_f32_e32 v180, v180
	v_rsq_f32_e32 v181, v181
	v_rsq_f32_e32 v182, v182
	v_rsq_f32_e32 v183, v183
	v_add_u32_e32 v211, 0x0, v210
	v_pk_mul_f32 v[124:125], v[124:125], v[176:177] op_sel_hi:[1,0]
	v_pk_mul_f32 v[126:127], v[126:127], v[176:177] op_sel_hi:[1,0]
	v_pk_mul_f32 v[124:125], v[124:125], v[184:185]
	v_pk_mul_f32 v[126:127], v[126:127], v[186:187]
	global_store_dwordx4 v211, v[124:127], s[90:91] offset:0
	v_pk_mul_f32 v[120:121], v[120:121], v[176:177] op_sel_hi:[1,0]
	v_pk_mul_f32 v[122:123], v[122:123], v[176:177] op_sel_hi:[1,0]
	v_pk_mul_f32 v[120:121], v[120:121], v[188:189]
	v_pk_mul_f32 v[122:123], v[122:123], v[190:191]
	global_store_dwordx4 v211, v[120:123], s[90:91] offset:16
	v_pk_mul_f32 v[116:117], v[116:117], v[176:177] op_sel_hi:[1,0]
	v_pk_mul_f32 v[118:119], v[118:119], v[176:177] op_sel_hi:[1,0]
	v_pk_mul_f32 v[116:117], v[116:117], v[192:193]
	v_pk_mul_f32 v[118:119], v[118:119], v[194:195]
	global_store_dwordx4 v211, v[116:119], s[90:91] offset:512
	v_pk_mul_f32 v[112:113], v[112:113], v[176:177] op_sel_hi:[1,0]
	v_pk_mul_f32 v[114:115], v[114:115], v[176:177] op_sel_hi:[1,0]
	v_pk_mul_f32 v[112:113], v[112:113], v[196:197]
	v_pk_mul_f32 v[114:115], v[114:115], v[198:199]
	global_store_dwordx4 v211, v[112:115], s[90:91] offset:528
	v_add_u32_e32 v211, 0x20000, v210
	v_pk_mul_f32 v[108:109], v[108:109], v[176:177] op_sel:[0,1] op_sel_hi:[1,1]
	v_pk_mul_f32 v[110:111], v[110:111], v[176:177] op_sel:[0,1] op_sel_hi:[1,1]
	v_pk_mul_f32 v[108:109], v[108:109], v[184:185]
	v_pk_mul_f32 v[110:111], v[110:111], v[186:187]
	global_store_dwordx4 v211, v[108:111], s[90:91] offset:0
	v_pk_mul_f32 v[104:105], v[104:105], v[176:177] op_sel:[0,1] op_sel_hi:[1,1]
	v_pk_mul_f32 v[106:107], v[106:107], v[176:177] op_sel:[0,1] op_sel_hi:[1,1]
	v_pk_mul_f32 v[104:105], v[104:105], v[188:189]
	v_pk_mul_f32 v[106:107], v[106:107], v[190:191]
	global_store_dwordx4 v211, v[104:107], s[90:91] offset:16
	v_pk_mul_f32 v[100:101], v[100:101], v[176:177] op_sel:[0,1] op_sel_hi:[1,1]
	v_pk_mul_f32 v[102:103], v[102:103], v[176:177] op_sel:[0,1] op_sel_hi:[1,1]
	v_pk_mul_f32 v[100:101], v[100:101], v[192:193]
	v_pk_mul_f32 v[102:103], v[102:103], v[194:195]
	global_store_dwordx4 v211, v[100:103], s[90:91] offset:512
	v_pk_mul_f32 v[96:97], v[96:97], v[176:177] op_sel:[0,1] op_sel_hi:[1,1]
	v_pk_mul_f32 v[98:99], v[98:99], v[176:177] op_sel:[0,1] op_sel_hi:[1,1]
	v_pk_mul_f32 v[96:97], v[96:97], v[196:197]
	v_pk_mul_f32 v[98:99], v[98:99], v[198:199]
	global_store_dwordx4 v211, v[96:99], s[90:91] offset:528
	v_add_u32_e32 v211, 0x40000, v210
	v_pk_mul_f32 v[92:93], v[92:93], v[178:179] op_sel_hi:[1,0]
	v_pk_mul_f32 v[94:95], v[94:95], v[178:179] op_sel_hi:[1,0]
	v_pk_mul_f32 v[92:93], v[92:93], v[184:185]
	v_pk_mul_f32 v[94:95], v[94:95], v[186:187]
	global_store_dwordx4 v211, v[92:95], s[90:91] offset:0
	v_pk_mul_f32 v[88:89], v[88:89], v[178:179] op_sel_hi:[1,0]
	v_pk_mul_f32 v[90:91], v[90:91], v[178:179] op_sel_hi:[1,0]
	v_pk_mul_f32 v[88:89], v[88:89], v[188:189]
	v_pk_mul_f32 v[90:91], v[90:91], v[190:191]
	global_store_dwordx4 v211, v[88:91], s[90:91] offset:16
	v_pk_mul_f32 v[84:85], v[84:85], v[178:179] op_sel_hi:[1,0]
	v_pk_mul_f32 v[86:87], v[86:87], v[178:179] op_sel_hi:[1,0]
	v_pk_mul_f32 v[84:85], v[84:85], v[192:193]
	v_pk_mul_f32 v[86:87], v[86:87], v[194:195]
	global_store_dwordx4 v211, v[84:87], s[90:91] offset:512
	v_pk_mul_f32 v[80:81], v[80:81], v[178:179] op_sel_hi:[1,0]
	v_pk_mul_f32 v[82:83], v[82:83], v[178:179] op_sel_hi:[1,0]
	v_pk_mul_f32 v[80:81], v[80:81], v[196:197]
	v_pk_mul_f32 v[82:83], v[82:83], v[198:199]
	global_store_dwordx4 v211, v[80:83], s[90:91] offset:528
	v_add_u32_e32 v211, 0x60000, v210
	v_pk_mul_f32 v[76:77], v[76:77], v[178:179] op_sel:[0,1] op_sel_hi:[1,1]
	v_pk_mul_f32 v[78:79], v[78:79], v[178:179] op_sel:[0,1] op_sel_hi:[1,1]
	v_pk_mul_f32 v[76:77], v[76:77], v[184:185]
	v_pk_mul_f32 v[78:79], v[78:79], v[186:187]
	global_store_dwordx4 v211, v[76:79], s[90:91] offset:0
	v_pk_mul_f32 v[72:73], v[72:73], v[178:179] op_sel:[0,1] op_sel_hi:[1,1]
	v_pk_mul_f32 v[74:75], v[74:75], v[178:179] op_sel:[0,1] op_sel_hi:[1,1]
	v_pk_mul_f32 v[72:73], v[72:73], v[188:189]
	v_pk_mul_f32 v[74:75], v[74:75], v[190:191]
	global_store_dwordx4 v211, v[72:75], s[90:91] offset:16
	v_pk_mul_f32 v[68:69], v[68:69], v[178:179] op_sel:[0,1] op_sel_hi:[1,1]
	v_pk_mul_f32 v[70:71], v[70:71], v[178:179] op_sel:[0,1] op_sel_hi:[1,1]
	v_pk_mul_f32 v[68:69], v[68:69], v[192:193]
	v_pk_mul_f32 v[70:71], v[70:71], v[194:195]
	global_store_dwordx4 v211, v[68:71], s[90:91] offset:512
	v_pk_mul_f32 v[64:65], v[64:65], v[178:179] op_sel:[0,1] op_sel_hi:[1,1]
	v_pk_mul_f32 v[66:67], v[66:67], v[178:179] op_sel:[0,1] op_sel_hi:[1,1]
	v_pk_mul_f32 v[64:65], v[64:65], v[196:197]
	v_pk_mul_f32 v[66:67], v[66:67], v[198:199]
	global_store_dwordx4 v211, v[64:67], s[90:91] offset:528
	v_add_u32_e32 v211, 0x100000, v210
	v_pk_mul_f32 v[60:61], v[60:61], v[180:181] op_sel_hi:[1,0]
	v_pk_mul_f32 v[62:63], v[62:63], v[180:181] op_sel_hi:[1,0]
	v_pk_mul_f32 v[60:61], v[60:61], v[184:185]
	v_pk_mul_f32 v[62:63], v[62:63], v[186:187]
	global_store_dwordx4 v211, v[60:63], s[90:91] offset:0
	v_pk_mul_f32 v[56:57], v[56:57], v[180:181] op_sel_hi:[1,0]
	v_pk_mul_f32 v[58:59], v[58:59], v[180:181] op_sel_hi:[1,0]
	v_pk_mul_f32 v[56:57], v[56:57], v[188:189]
	v_pk_mul_f32 v[58:59], v[58:59], v[190:191]
	global_store_dwordx4 v211, v[56:59], s[90:91] offset:16
	v_pk_mul_f32 v[52:53], v[52:53], v[180:181] op_sel_hi:[1,0]
	v_pk_mul_f32 v[54:55], v[54:55], v[180:181] op_sel_hi:[1,0]
	v_pk_mul_f32 v[52:53], v[52:53], v[192:193]
	v_pk_mul_f32 v[54:55], v[54:55], v[194:195]
	global_store_dwordx4 v211, v[52:55], s[90:91] offset:512
	v_pk_mul_f32 v[48:49], v[48:49], v[180:181] op_sel_hi:[1,0]
	v_pk_mul_f32 v[50:51], v[50:51], v[180:181] op_sel_hi:[1,0]
	v_pk_mul_f32 v[48:49], v[48:49], v[196:197]
	v_pk_mul_f32 v[50:51], v[50:51], v[198:199]
	global_store_dwordx4 v211, v[48:51], s[90:91] offset:528
	v_add_u32_e32 v211, 0x120000, v210
	v_pk_mul_f32 v[44:45], v[44:45], v[180:181] op_sel:[0,1] op_sel_hi:[1,1]
	v_pk_mul_f32 v[46:47], v[46:47], v[180:181] op_sel:[0,1] op_sel_hi:[1,1]
	v_pk_mul_f32 v[44:45], v[44:45], v[184:185]
	v_pk_mul_f32 v[46:47], v[46:47], v[186:187]
	global_store_dwordx4 v211, v[44:47], s[90:91] offset:0
	v_pk_mul_f32 v[40:41], v[40:41], v[180:181] op_sel:[0,1] op_sel_hi:[1,1]
	v_pk_mul_f32 v[42:43], v[42:43], v[180:181] op_sel:[0,1] op_sel_hi:[1,1]
	v_pk_mul_f32 v[40:41], v[40:41], v[188:189]
	v_pk_mul_f32 v[42:43], v[42:43], v[190:191]
	global_store_dwordx4 v211, v[40:43], s[90:91] offset:16
	v_pk_mul_f32 v[36:37], v[36:37], v[180:181] op_sel:[0,1] op_sel_hi:[1,1]
	v_pk_mul_f32 v[38:39], v[38:39], v[180:181] op_sel:[0,1] op_sel_hi:[1,1]
	v_pk_mul_f32 v[36:37], v[36:37], v[192:193]
	v_pk_mul_f32 v[38:39], v[38:39], v[194:195]
	global_store_dwordx4 v211, v[36:39], s[90:91] offset:512
	v_pk_mul_f32 v[32:33], v[32:33], v[180:181] op_sel:[0,1] op_sel_hi:[1,1]
	v_pk_mul_f32 v[34:35], v[34:35], v[180:181] op_sel:[0,1] op_sel_hi:[1,1]
	v_pk_mul_f32 v[32:33], v[32:33], v[196:197]
	v_pk_mul_f32 v[34:35], v[34:35], v[198:199]
	global_store_dwordx4 v211, v[32:35], s[90:91] offset:528
	v_add_u32_e32 v211, 0x140000, v210
	v_pk_mul_f32 v[28:29], v[28:29], v[182:183] op_sel_hi:[1,0]
	v_pk_mul_f32 v[30:31], v[30:31], v[182:183] op_sel_hi:[1,0]
	v_pk_mul_f32 v[28:29], v[28:29], v[184:185]
	v_pk_mul_f32 v[30:31], v[30:31], v[186:187]
	global_store_dwordx4 v211, v[28:31], s[90:91] offset:0
	v_pk_mul_f32 v[24:25], v[24:25], v[182:183] op_sel_hi:[1,0]
	v_pk_mul_f32 v[26:27], v[26:27], v[182:183] op_sel_hi:[1,0]
	v_pk_mul_f32 v[24:25], v[24:25], v[188:189]
	v_pk_mul_f32 v[26:27], v[26:27], v[190:191]
	global_store_dwordx4 v211, v[24:27], s[90:91] offset:16
	v_pk_mul_f32 v[20:21], v[20:21], v[182:183] op_sel_hi:[1,0]
	v_pk_mul_f32 v[22:23], v[22:23], v[182:183] op_sel_hi:[1,0]
	v_pk_mul_f32 v[20:21], v[20:21], v[192:193]
	v_pk_mul_f32 v[22:23], v[22:23], v[194:195]
	global_store_dwordx4 v211, v[20:23], s[90:91] offset:512
	v_pk_mul_f32 v[16:17], v[16:17], v[182:183] op_sel_hi:[1,0]
	v_pk_mul_f32 v[18:19], v[18:19], v[182:183] op_sel_hi:[1,0]
	v_pk_mul_f32 v[16:17], v[16:17], v[196:197]
	v_pk_mul_f32 v[18:19], v[18:19], v[198:199]
	global_store_dwordx4 v211, v[16:19], s[90:91] offset:528
	v_add_u32_e32 v211, 0x160000, v210
	v_pk_mul_f32 v[12:13], v[12:13], v[182:183] op_sel:[0,1] op_sel_hi:[1,1]
	v_pk_mul_f32 v[14:15], v[14:15], v[182:183] op_sel:[0,1] op_sel_hi:[1,1]
	v_pk_mul_f32 v[12:13], v[12:13], v[184:185]
	v_pk_mul_f32 v[14:15], v[14:15], v[186:187]
	global_store_dwordx4 v211, v[12:15], s[90:91] offset:0
	v_pk_mul_f32 v[8:9], v[8:9], v[182:183] op_sel:[0,1] op_sel_hi:[1,1]
	v_pk_mul_f32 v[10:11], v[10:11], v[182:183] op_sel:[0,1] op_sel_hi:[1,1]
	v_pk_mul_f32 v[8:9], v[8:9], v[188:189]
	v_pk_mul_f32 v[10:11], v[10:11], v[190:191]
	global_store_dwordx4 v211, v[8:11], s[90:91] offset:16
	v_pk_mul_f32 v[4:5], v[4:5], v[182:183] op_sel:[0,1] op_sel_hi:[1,1]
	v_pk_mul_f32 v[6:7], v[6:7], v[182:183] op_sel:[0,1] op_sel_hi:[1,1]
	v_pk_mul_f32 v[4:5], v[4:5], v[192:193]
	v_pk_mul_f32 v[6:7], v[6:7], v[194:195]
	global_store_dwordx4 v211, v[4:7], s[90:91] offset:512
	v_pk_mul_f32 v[0:1], v[0:1], v[182:183] op_sel:[0,1] op_sel_hi:[1,1]
	v_pk_mul_f32 v[2:3], v[2:3], v[182:183] op_sel:[0,1] op_sel_hi:[1,1]
	v_pk_mul_f32 v[0:1], v[0:1], v[196:197]
	v_pk_mul_f32 v[2:3], v[2:3], v[198:199]
	global_store_dwordx4 v211, v[0:3], s[90:91] offset:528
	s_branch .LBB0_973

.LBB0_1057:
	s_or_b64 exec, exec, s[0:1]
	v_readlane_b32 s0, v255, 2
	v_readlane_b32 s1, v255, 3
	s_andn2_b64 vcc, exec, s[0:1]
	s_waitcnt lgkmcnt(0)
	s_barrier
	s_branch .LBB0_1060
	v_mov_b32_e32 v163, 0
	v_lshl_add_u64 v[0:1], s[88:89], 0, v[162:163]
	s_mov_b64 s[0:1], 0x1400
	v_lshl_add_u64 v[4:5], v[0:1], 0, s[0:1]
	s_mov_b64 s[0:1], 0x1800
	v_lshl_add_u64 v[6:7], v[0:1], 0, s[0:1]
	s_mov_b64 s[0:1], 0x1c00
	s_ashr_i32 s79, s78, 31
	v_lshl_add_u64 v[8:9], v[0:1], 0, s[0:1]
	s_lshl_b64 s[0:1], s[78:79], 2
	s_add_u32 s0, s92, s0
	s_addc_u32 s1, s93, s1
	v_readlane_b32 s8, v255, 0
	s_add_u32 s0, s0, 0x50000
	v_readlane_b32 s9, v255, 1
	s_addc_u32 s1, s1, 0
	s_ashr_i32 s9, s8, 31
	s_lshl_b64 s[2:3], s[8:9], 2
	s_lshl_b64 s[6:7], s[78:79], 13
	s_add_u32 s6, s90, s6
	s_addc_u32 s7, s91, s7
	s_mov_b64 s[4:5], 0x1000
	s_waitcnt vmcnt(4)
	v_lshl_add_u64 v[10:11], s[6:7], 0, v[162:163]
	v_lshl_add_u64 v[2:3], v[0:1], 0, s[4:5]
	v_lshl_add_u64 v[10:11], v[10:11], 0, s[4:5]
	s_lshl_b64 s[4:5], s[8:9], 13
	v_mov_b32_e32 v12, 0x3727c5ac
